# P5: removed the epilogue's b_sp vmcnt waits that forced the next unit's raw-row prefetch to complete (b_sp is drained at the loop top); last-iteration path keeps a vmcnt(0)
# speedup vs baseline: 1.0103x; 1.0018x over previous
; __device__ __forceinline__ unsigned cvtpk(float lo, float hi) { unsigned r; asm volatile("v_cvt_pk_bf16_f32 %0, %1, %2" : "=v"(r) : "v"(lo), "v"(hi)); return r; }
; __device__ __forceinline__ int crow(int r, int hi) { return (r & 3) + 8 * (r >> 2) + 4 * hi; }
; __device__ __forceinline__ void spatial_phase(const Params& p, char* lds) {
;     ...
; #pragma unroll
;             for (int r = 0; r < 16; ++r) { const int tl = crow(r, hi); const float bsp = bsp_[r];
; #pragma unroll
;                 for (int d0 = 0; d0 < 4; ++d0) { const unsigned pk = cvtpk(o[d0][r] + bsp, 0.f); *(bf16_t*)(stg + tl * 256 + (d0 * 32 + r32) * 2) = (bf16_t)(pk & 0xffffu); } }
;             asm volatile("s_waitcnt lgkmcnt(0)" ::: "memory");
.LBB0_1266:
	v_add_f32_e32 v0, v164, v0
	v_cvt_pk_bf16_f32 v0, v0, v96
	ds_write_b16 v189, v0
	s_nop 0
	v_add_f32_e32 v0, v164, v16
	v_cvt_pk_bf16_f32 v0, v0, v96
	ds_write_b16 v189, v0 offset:64
	s_nop 1
	v_add_f32_e32 v0, v164, v32
	v_cvt_pk_bf16_f32 v0, v0, v96
	ds_write_b16 v189, v0 offset:128
	s_nop 1
	v_add_f32_e32 v0, v164, v48
	v_cvt_pk_bf16_f32 v0, v0, v96
	ds_write_b16 v189, v0 offset:192
	v_add_f32_e32 v0, v165, v1
	v_cvt_pk_bf16_f32 v0, v0, v96
	ds_write_b16 v189, v0 offset:256
	v_add_f32_e32 v0, v165, v17
	v_cvt_pk_bf16_f32 v0, v0, v96
	ds_write_b16 v189, v0 offset:320
	v_add_f32_e32 v0, v165, v33
	v_cvt_pk_bf16_f32 v0, v0, v96
	ds_write_b16 v189, v0 offset:384
	v_add_f32_e32 v0, v165, v49
	v_cvt_pk_bf16_f32 v0, v0, v96
	ds_write_b16 v189, v0 offset:448
	v_add_f32_e32 v0, v166, v2
	v_cvt_pk_bf16_f32 v0, v0, v96
	ds_write_b16 v189, v0 offset:512
	v_add_f32_e32 v0, v166, v18
	v_cvt_pk_bf16_f32 v0, v0, v96
	ds_write_b16 v189, v0 offset:576
	v_add_f32_e32 v0, v166, v34
	v_cvt_pk_bf16_f32 v0, v0, v96
	ds_write_b16 v189, v0 offset:640
	v_add_f32_e32 v0, v166, v50
	v_cvt_pk_bf16_f32 v0, v0, v96
	ds_write_b16 v189, v0 offset:704
	v_add_f32_e32 v0, v167, v3
	v_cvt_pk_bf16_f32 v0, v0, v96
	ds_write_b16 v189, v0 offset:768
	v_add_f32_e32 v0, v167, v19
	v_cvt_pk_bf16_f32 v0, v0, v96
	ds_write_b16 v189, v0 offset:832
	v_add_f32_e32 v0, v167, v35
	v_cvt_pk_bf16_f32 v0, v0, v96
	ds_write_b16 v189, v0 offset:896
	v_add_f32_e32 v0, v167, v51
	v_cvt_pk_bf16_f32 v0, v0, v96
	ds_write_b16 v189, v0 offset:960
	v_add_f32_e32 v0, v168, v4
	v_cvt_pk_bf16_f32 v0, v0, v96
	ds_write_b16 v189, v0 offset:2048
	v_add_f32_e32 v0, v168, v20
	v_cvt_pk_bf16_f32 v0, v0, v96
	ds_write_b16 v189, v0 offset:2112
	v_add_f32_e32 v0, v168, v36
	v_cvt_pk_bf16_f32 v0, v0, v96
	ds_write_b16 v189, v0 offset:2176
	v_add_f32_e32 v0, v168, v52
	v_cvt_pk_bf16_f32 v0, v0, v96
	ds_write_b16 v189, v0 offset:2240
	v_add_f32_e32 v0, v169, v5
	v_cvt_pk_bf16_f32 v0, v0, v96
	ds_write_b16 v189, v0 offset:2304
	v_add_f32_e32 v0, v169, v21
	v_cvt_pk_bf16_f32 v0, v0, v96
	ds_write_b16 v189, v0 offset:2368
	v_add_f32_e32 v0, v169, v37
	v_cvt_pk_bf16_f32 v0, v0, v96
	ds_write_b16 v189, v0 offset:2432
	v_add_f32_e32 v0, v169, v53
	v_cvt_pk_bf16_f32 v0, v0, v96
	ds_write_b16 v189, v0 offset:2496
	v_add_f32_e32 v0, v170, v6
	v_cvt_pk_bf16_f32 v0, v0, v96
	ds_write_b16 v189, v0 offset:2560
	v_add_f32_e32 v0, v170, v22
	v_cvt_pk_bf16_f32 v0, v0, v96
	ds_write_b16 v189, v0 offset:2624
	v_add_f32_e32 v0, v170, v38
	v_cvt_pk_bf16_f32 v0, v0, v96
	ds_write_b16 v189, v0 offset:2688
	v_add_f32_e32 v0, v170, v54
	v_cvt_pk_bf16_f32 v0, v0, v96
	ds_write_b16 v189, v0 offset:2752
	v_add_f32_e32 v0, v171, v7
	v_cvt_pk_bf16_f32 v0, v0, v96
	ds_write_b16 v189, v0 offset:2816
	v_add_f32_e32 v0, v171, v23
	v_cvt_pk_bf16_f32 v0, v0, v96
	ds_write_b16 v189, v0 offset:2880
	v_add_f32_e32 v0, v171, v39
	v_cvt_pk_bf16_f32 v0, v0, v96
	ds_write_b16 v189, v0 offset:2944
	v_add_f32_e32 v0, v171, v55
	v_cvt_pk_bf16_f32 v0, v0, v96
	ds_write_b16 v189, v0 offset:3008
	v_add_f32_e32 v0, v172, v8
	v_cvt_pk_bf16_f32 v0, v0, v96
	ds_write_b16 v189, v0 offset:4096
	v_add_f32_e32 v0, v172, v24
	v_cvt_pk_bf16_f32 v0, v0, v96
	ds_write_b16 v189, v0 offset:4160
	v_add_f32_e32 v0, v172, v40
	v_cvt_pk_bf16_f32 v0, v0, v96
	ds_write_b16 v189, v0 offset:4224
	v_add_f32_e32 v0, v172, v56
	v_cvt_pk_bf16_f32 v0, v0, v96
	ds_write_b16 v189, v0 offset:4288
	v_add_f32_e32 v0, v173, v9
	v_cvt_pk_bf16_f32 v0, v0, v96
	ds_write_b16 v189, v0 offset:4352
	v_add_f32_e32 v0, v173, v25
	v_cvt_pk_bf16_f32 v0, v0, v96
	ds_write_b16 v189, v0 offset:4416
	v_add_f32_e32 v0, v173, v41
	v_cvt_pk_bf16_f32 v0, v0, v96
	ds_write_b16 v189, v0 offset:4480
	v_add_f32_e32 v0, v173, v57
	v_cvt_pk_bf16_f32 v0, v0, v96
	ds_write_b16 v189, v0 offset:4544
	v_add_f32_e32 v0, v174, v10
	v_cvt_pk_bf16_f32 v0, v0, v96
	ds_write_b16 v189, v0 offset:4608
	v_add_f32_e32 v0, v174, v26
	v_cvt_pk_bf16_f32 v0, v0, v96
	ds_write_b16 v189, v0 offset:4672
	v_add_f32_e32 v0, v174, v42
	v_cvt_pk_bf16_f32 v0, v0, v96
	ds_write_b16 v189, v0 offset:4736
	v_add_f32_e32 v0, v174, v58
	v_cvt_pk_bf16_f32 v0, v0, v96
	ds_write_b16 v189, v0 offset:4800
	v_add_f32_e32 v0, v175, v11
	v_cvt_pk_bf16_f32 v0, v0, v96
	ds_write_b16 v189, v0 offset:4864
	v_add_f32_e32 v0, v175, v27
	v_cvt_pk_bf16_f32 v0, v0, v96
	ds_write_b16 v189, v0 offset:4928
	v_add_f32_e32 v0, v175, v43
	v_cvt_pk_bf16_f32 v0, v0, v96
	ds_write_b16 v189, v0 offset:4992
	v_add_f32_e32 v0, v175, v59
	v_cvt_pk_bf16_f32 v0, v0, v96
	ds_write_b16 v189, v0 offset:5056
	v_add_f32_e32 v0, v176, v12
	v_cvt_pk_bf16_f32 v0, v0, v96
	ds_write_b16 v189, v0 offset:6144
	v_add_f32_e32 v0, v176, v28
	v_cvt_pk_bf16_f32 v0, v0, v96
	ds_write_b16 v189, v0 offset:6208
	v_add_f32_e32 v0, v176, v44
	v_cvt_pk_bf16_f32 v0, v0, v96
	ds_write_b16 v189, v0 offset:6272
	v_add_f32_e32 v0, v176, v60
	v_cvt_pk_bf16_f32 v0, v0, v96
	ds_write_b16 v189, v0 offset:6336
	v_add_f32_e32 v0, v177, v13
	v_cvt_pk_bf16_f32 v0, v0, v96
	ds_write_b16 v189, v0 offset:6400
	v_add_f32_e32 v0, v177, v29
	v_cvt_pk_bf16_f32 v0, v0, v96
	ds_write_b16 v189, v0 offset:6464
	v_add_f32_e32 v0, v177, v45
	v_cvt_pk_bf16_f32 v0, v0, v96
	ds_write_b16 v189, v0 offset:6528
	v_add_f32_e32 v0, v177, v61
	v_cvt_pk_bf16_f32 v0, v0, v96
	ds_write_b16 v189, v0 offset:6592
	v_add_f32_e32 v0, v178, v14
	v_cvt_pk_bf16_f32 v0, v0, v96
	ds_write_b16 v189, v0 offset:6656
	v_add_f32_e32 v0, v178, v30
	v_cvt_pk_bf16_f32 v0, v0, v96
	ds_write_b16 v189, v0 offset:6720
	v_add_f32_e32 v0, v178, v46
	v_cvt_pk_bf16_f32 v0, v0, v96
	ds_write_b16 v189, v0 offset:6784
	v_add_f32_e32 v0, v178, v62
	v_cvt_pk_bf16_f32 v0, v0, v96
	ds_write_b16 v189, v0 offset:6848
	v_add_f32_e32 v0, v179, v15
	v_cvt_pk_bf16_f32 v0, v0, v96
	ds_write_b16 v189, v0 offset:6912
	v_add_f32_e32 v0, v179, v31
	v_cvt_pk_bf16_f32 v0, v0, v96
	ds_write_b16 v189, v0 offset:6976
	v_add_f32_e32 v0, v179, v47
	v_cvt_pk_bf16_f32 v0, v0, v96
	ds_write_b16 v189, v0 offset:7040
	v_add_f32_e32 v0, v179, v63
	v_cvt_pk_bf16_f32 v0, v0, v96
	ds_write_b16 v189, v0 offset:7104
	s_waitcnt lgkmcnt(0)
; __device__ __forceinline__ float bf2f(short s) { return __uint_as_float(((unsigned)(unsigned short)s) << 16); }
; __device__ __forceinline__ bf16x8 tobf8(f32x8 x) { u32x4 w = {cvtpk(x[0], x[1]), cvtpk(x[2], x[3]), cvtpk(x[4], x[5]), cvtpk(x[6], x[7])}; return *reinterpret_cast<bf16x8*>(&w); }
; __device__ __forceinline__ void spatial_phase(const Params& p, char* lds) {
;     ...
;             asm volatile("s_waitcnt lgkmcnt(0)" ::: "memory");
; #pragma unroll
;             for (int it = 0; it < 8; ++it) if (it < nit) { const int tl = it * 4 + er; const size_t row = rbase + 32 * tb + tl; const int col = g * GD + ch * 128 + ec;
;                 const bf16x8 mx = *(const bf16x8*)(stg + tl * 256 + ec * 2); f32x8 y;
; #pragma unroll
;                 for (int i = 0; i < 8; ++i) y[i] = bf2f(uu[it][i]) * bf2f(mx[i]);
;                 *(bf16x8*)(ACT + row * CW + col) = tobf8(y); }
;         }
;         __syncthreads();
	ds_read_b128 v[2:5], v226
	v_lshlrev_b32_e32 v7, 16, v120
	v_lshlrev_b32_e32 v8, 16, v121
	v_lshlrev_b32_e32 v9, 16, v122
	v_lshlrev_b32_e32 v10, 16, v123
	s_waitcnt lgkmcnt(0)
	v_lshlrev_b32_e32 v6, 16, v2
	v_mul_f32_e32 v6, v6, v7
	v_and_b32_e32 v7, 0xffff0000, v120
	v_and_b32_e32 v2, 0xffff0000, v2
	v_mul_f32_e32 v2, v2, v7
	v_lshlrev_b32_e32 v7, 16, v3
	v_mul_f32_e32 v7, v7, v8
	v_and_b32_e32 v8, 0xffff0000, v121
	v_and_b32_e32 v3, 0xffff0000, v3
	v_mul_f32_e32 v3, v3, v8
	v_lshlrev_b32_e32 v8, 16, v4
	v_mul_f32_e32 v8, v8, v9
	v_and_b32_e32 v9, 0xffff0000, v122
	v_and_b32_e32 v4, 0xffff0000, v4
	v_mul_f32_e32 v4, v4, v9
	v_lshlrev_b32_e32 v9, 16, v5
	v_mul_f32_e32 v9, v9, v10
	v_and_b32_e32 v10, 0xffff0000, v123
	v_and_b32_e32 v5, 0xffff0000, v5
	v_mul_f32_e32 v5, v5, v10
	s_add_u32 s40, s66, s48
	v_cvt_pk_bf16_f32 v2, v6, v2
	v_cvt_pk_bf16_f32 v3, v7, v3
	v_cvt_pk_bf16_f32 v4, v8, v4
	v_cvt_pk_bf16_f32 v5, v9, v5
	ds_read_b128 v[6:9], v227
	s_addc_u32 s41, s67, 0
	v_add_lshl_u32 v0, v195, s80, 1
	v_mov_b32_e32 v1, v96
	v_mov_b32_e32 v11, s41
	v_or_b32_e32 v10, s40, v188
	v_lshl_add_u64 v[0:1], s[86:87], 0, v[0:1]
	v_lshlrev_b64 v[10:11], 13, v[10:11]
	v_lshl_add_u64 v[10:11], v[0:1], 0, v[10:11]
	global_store_dwordx4 v[10:11], v[2:5], off
	v_lshlrev_b32_e32 v10, 16, v119
	v_mov_b32_e32 v11, s41
	s_waitcnt lgkmcnt(0)
	v_lshlrev_b32_e32 v2, 16, v6
	v_lshlrev_b32_e32 v3, 16, v116
	v_mul_f32_e32 v2, v2, v3
	v_and_b32_e32 v3, 0xffff0000, v116
	v_and_b32_e32 v4, 0xffff0000, v6
	v_mul_f32_e32 v3, v4, v3
	v_lshlrev_b32_e32 v4, 16, v7
	v_lshlrev_b32_e32 v5, 16, v117
	v_mul_f32_e32 v4, v4, v5
	v_and_b32_e32 v5, 0xffff0000, v117
	v_and_b32_e32 v6, 0xffff0000, v7
	v_mul_f32_e32 v5, v6, v5
	v_lshlrev_b32_e32 v6, 16, v8
	v_lshlrev_b32_e32 v7, 16, v118
	v_mul_f32_e32 v6, v6, v7
	v_and_b32_e32 v7, 0xffff0000, v118
	v_and_b32_e32 v8, 0xffff0000, v8
	v_mul_f32_e32 v7, v8, v7
	v_lshlrev_b32_e32 v8, 16, v9
	v_mul_f32_e32 v8, v8, v10
	v_and_b32_e32 v10, 0xffff0000, v119
	v_and_b32_e32 v9, 0xffff0000, v9
	v_mul_f32_e32 v9, v9, v10
	v_cvt_pk_bf16_f32 v2, v2, v3
	v_cvt_pk_bf16_f32 v3, v4, v5
	v_cvt_pk_bf16_f32 v4, v6, v7
	v_cvt_pk_bf16_f32 v5, v8, v9
	ds_read_b128 v[6:9], v228
	v_or_b32_e32 v10, s40, v206
	v_lshlrev_b64 v[10:11], 13, v[10:11]
	v_lshl_add_u64 v[10:11], v[0:1], 0, v[10:11]
	global_store_dwordx4 v[10:11], v[2:5], off
	v_lshlrev_b32_e32 v10, 16, v131
	v_mov_b32_e32 v11, s41
	s_waitcnt lgkmcnt(0)
	v_lshlrev_b32_e32 v2, 16, v6
	v_lshlrev_b32_e32 v3, 16, v128
	v_mul_f32_e32 v2, v2, v3
	v_and_b32_e32 v3, 0xffff0000, v128
	v_and_b32_e32 v4, 0xffff0000, v6
	v_mul_f32_e32 v3, v4, v3
	v_lshlrev_b32_e32 v4, 16, v7
	v_lshlrev_b32_e32 v5, 16, v129
	v_mul_f32_e32 v4, v4, v5
	v_and_b32_e32 v5, 0xffff0000, v129
	v_and_b32_e32 v6, 0xffff0000, v7
	v_mul_f32_e32 v5, v6, v5
	v_lshlrev_b32_e32 v6, 16, v8
	v_lshlrev_b32_e32 v7, 16, v130
	v_mul_f32_e32 v6, v6, v7
	v_and_b32_e32 v7, 0xffff0000, v130
	v_and_b32_e32 v8, 0xffff0000, v8
	v_mul_f32_e32 v7, v8, v7
	v_lshlrev_b32_e32 v8, 16, v9
	v_mul_f32_e32 v8, v8, v10
	v_and_b32_e32 v10, 0xffff0000, v131
	v_and_b32_e32 v9, 0xffff0000, v9
	v_mul_f32_e32 v9, v9, v10
	v_cvt_pk_bf16_f32 v2, v2, v3
	v_cvt_pk_bf16_f32 v3, v4, v5
	v_cvt_pk_bf16_f32 v4, v6, v7
	v_cvt_pk_bf16_f32 v5, v8, v9
	ds_read_b128 v[6:9], v229
	v_or_b32_e32 v10, s40, v208
	v_lshlrev_b64 v[10:11], 13, v[10:11]
	v_lshl_add_u64 v[10:11], v[0:1], 0, v[10:11]
	global_store_dwordx4 v[10:11], v[2:5], off
	s_and_b64 vcc, exec, s[38:39]
	s_waitcnt lgkmcnt(0)
	v_lshlrev_b32_e32 v2, 16, v6
	v_lshlrev_b32_e32 v3, 16, v124
	v_mul_f32_e32 v2, v2, v3
	v_and_b32_e32 v3, 0xffff0000, v124
	v_and_b32_e32 v4, 0xffff0000, v6
	v_mul_f32_e32 v3, v4, v3
	v_lshlrev_b32_e32 v4, 16, v7
	v_lshlrev_b32_e32 v5, 16, v125
	v_mul_f32_e32 v4, v4, v5
	v_and_b32_e32 v5, 0xffff0000, v125
	v_and_b32_e32 v6, 0xffff0000, v7
	v_mul_f32_e32 v5, v6, v5
	v_lshlrev_b32_e32 v6, 16, v8
	v_lshlrev_b32_e32 v7, 16, v126
	v_mul_f32_e32 v10, v6, v7
	v_and_b32_e32 v6, 0xffff0000, v126
	v_and_b32_e32 v7, 0xffff0000, v8
	v_mul_f32_e32 v8, v7, v6
	v_lshlrev_b32_e32 v6, 16, v9
	v_lshlrev_b32_e32 v7, 16, v127
	v_mul_f32_e32 v11, v6, v7
	v_and_b32_e32 v6, 0xffff0000, v127
	v_and_b32_e32 v7, 0xffff0000, v9
	v_mul_f32_e32 v9, v7, v6
	v_mov_b32_e32 v7, s41
	v_or_b32_e32 v6, s40, v210
	v_lshlrev_b64 v[6:7], 13, v[6:7]
	v_lshl_add_u64 v[6:7], v[0:1], 0, v[6:7]
	v_cvt_pk_bf16_f32 v2, v2, v3
	v_cvt_pk_bf16_f32 v3, v4, v5
	v_cvt_pk_bf16_f32 v4, v10, v8
	v_cvt_pk_bf16_f32 v5, v11, v9
	global_store_dwordx4 v[6:7], v[2:5], off
	s_cbranch_vccnz .LBB0_1199
; __device__ __forceinline__ float bf2f(short s) { return __uint_as_float(((unsigned)(unsigned short)s) << 16); }
; __device__ __forceinline__ bf16x8 tobf8(f32x8 x) { u32x4 w = {cvtpk(x[0], x[1]), cvtpk(x[2], x[3]), cvtpk(x[4], x[5]), cvtpk(x[6], x[7])}; return *reinterpret_cast<bf16x8*>(&w); }
; __device__ __forceinline__ void spatial_phase(const Params& p, char* lds) {
;     ...
; #pragma unroll
;             for (int it = 0; it < 8; ++it) if (it < nit) { const int tl = it * 4 + er; const size_t row = rbase + 32 * tb + tl; const int col = g * GD + ch * 128 + ec;
;                 const bf16x8 mx = *(const bf16x8*)(stg + tl * 256 + ec * 2); f32x8 y;
; #pragma unroll
;                 for (int i = 0; i < 8; ++i) y[i] = bf2f(uu[it][i]) * bf2f(mx[i]);
;                 *(bf16x8*)(ACT + row * CW + col) = tobf8(y); }
;         }
;         __syncthreads();
	ds_read_b128 v[2:5], v230
	v_lshlrev_b32_e32 v7, 16, v112
	s_waitcnt lgkmcnt(0)
	v_lshlrev_b32_e32 v6, 16, v2
	v_mul_f32_e32 v8, v6, v7
	v_and_b32_e32 v6, 0xffff0000, v112
	v_and_b32_e32 v2, 0xffff0000, v2
	v_mul_f32_e32 v2, v2, v6
	v_lshlrev_b32_e32 v6, 16, v3
	v_lshlrev_b32_e32 v7, 16, v113
	v_mul_f32_e32 v9, v6, v7
	v_and_b32_e32 v6, 0xffff0000, v113
	v_and_b32_e32 v3, 0xffff0000, v3
	v_mul_f32_e32 v3, v3, v6
	v_lshlrev_b32_e32 v6, 16, v4
	v_lshlrev_b32_e32 v7, 16, v114
	v_mul_f32_e32 v10, v6, v7
	v_and_b32_e32 v6, 0xffff0000, v114
	v_and_b32_e32 v4, 0xffff0000, v4
	v_mul_f32_e32 v4, v4, v6
	v_lshlrev_b32_e32 v6, 16, v5
	v_lshlrev_b32_e32 v7, 16, v115
	v_mul_f32_e32 v11, v6, v7
	v_and_b32_e32 v6, 0xffff0000, v115
	v_and_b32_e32 v5, 0xffff0000, v5
	v_mul_f32_e32 v5, v5, v6
	v_lshl_add_u64 v[6:7], s[40:41], 0, v[212:213]
	v_lshlrev_b64 v[6:7], 13, v[6:7]
	v_cvt_pk_bf16_f32 v2, v8, v2
	v_cvt_pk_bf16_f32 v3, v9, v3
	v_cvt_pk_bf16_f32 v4, v10, v4
	v_cvt_pk_bf16_f32 v5, v11, v5
	v_lshl_add_u64 v[6:7], v[0:1], 0, v[6:7]
	global_store_dwordx4 v[6:7], v[2:5], off
	ds_read_b128 v[2:5], v231
	v_lshlrev_b32_e32 v7, 16, v108
	s_waitcnt lgkmcnt(0)
	v_lshlrev_b32_e32 v6, 16, v2
	v_mul_f32_e32 v8, v6, v7
	v_and_b32_e32 v6, 0xffff0000, v108
	v_and_b32_e32 v2, 0xffff0000, v2
	v_mul_f32_e32 v2, v2, v6
	v_lshlrev_b32_e32 v6, 16, v3
	v_lshlrev_b32_e32 v7, 16, v109
	v_mul_f32_e32 v9, v6, v7
	v_and_b32_e32 v6, 0xffff0000, v109
	v_and_b32_e32 v3, 0xffff0000, v3
	v_mul_f32_e32 v3, v3, v6
	v_lshlrev_b32_e32 v6, 16, v4
	v_lshlrev_b32_e32 v7, 16, v110
	v_mul_f32_e32 v10, v6, v7
	v_and_b32_e32 v6, 0xffff0000, v110
	v_and_b32_e32 v4, 0xffff0000, v4
	v_mul_f32_e32 v4, v4, v6
	v_lshlrev_b32_e32 v6, 16, v5
	v_lshlrev_b32_e32 v7, 16, v111
	v_mul_f32_e32 v11, v6, v7
	v_and_b32_e32 v6, 0xffff0000, v111
	v_and_b32_e32 v5, 0xffff0000, v5
	v_mul_f32_e32 v5, v5, v6
	v_lshl_add_u64 v[6:7], s[40:41], 0, v[214:215]
	v_lshlrev_b64 v[6:7], 13, v[6:7]
	v_cvt_pk_bf16_f32 v2, v8, v2
	v_cvt_pk_bf16_f32 v3, v9, v3
	v_cvt_pk_bf16_f32 v4, v10, v4
	v_cvt_pk_bf16_f32 v5, v11, v5
	v_lshl_add_u64 v[6:7], v[0:1], 0, v[6:7]
	global_store_dwordx4 v[6:7], v[2:5], off
	ds_read_b128 v[2:5], v232
	v_lshlrev_b32_e32 v7, 16, v104
	s_waitcnt lgkmcnt(0)
	v_lshlrev_b32_e32 v6, 16, v2
	v_mul_f32_e32 v8, v6, v7
	v_and_b32_e32 v6, 0xffff0000, v104
	v_and_b32_e32 v2, 0xffff0000, v2
	v_mul_f32_e32 v2, v2, v6
	v_lshlrev_b32_e32 v6, 16, v3
	v_lshlrev_b32_e32 v7, 16, v105
	v_mul_f32_e32 v9, v6, v7
	v_and_b32_e32 v6, 0xffff0000, v105
	v_and_b32_e32 v3, 0xffff0000, v3
	v_mul_f32_e32 v3, v3, v6
	v_lshlrev_b32_e32 v6, 16, v4
	v_lshlrev_b32_e32 v7, 16, v106
	v_mul_f32_e32 v10, v6, v7
	v_and_b32_e32 v6, 0xffff0000, v106
	v_and_b32_e32 v4, 0xffff0000, v4
	v_mul_f32_e32 v4, v4, v6
	v_lshlrev_b32_e32 v6, 16, v5
	v_lshlrev_b32_e32 v7, 16, v107
	v_mul_f32_e32 v11, v6, v7
	v_and_b32_e32 v6, 0xffff0000, v107
	v_and_b32_e32 v5, 0xffff0000, v5
	v_mul_f32_e32 v5, v5, v6
	v_lshl_add_u64 v[6:7], s[40:41], 0, v[216:217]
	v_lshlrev_b64 v[6:7], 13, v[6:7]
	v_cvt_pk_bf16_f32 v2, v8, v2
	v_cvt_pk_bf16_f32 v3, v9, v3
	v_cvt_pk_bf16_f32 v4, v10, v4
	v_cvt_pk_bf16_f32 v5, v11, v5
	v_lshl_add_u64 v[6:7], v[0:1], 0, v[6:7]
	global_store_dwordx4 v[6:7], v[2:5], off
	ds_read_b128 v[2:5], v233
	v_lshlrev_b32_e32 v7, 16, v100
	s_waitcnt lgkmcnt(0)
	v_lshlrev_b32_e32 v6, 16, v2
	v_mul_f32_e32 v8, v6, v7
	v_and_b32_e32 v6, 0xffff0000, v100
	v_and_b32_e32 v2, 0xffff0000, v2
	v_mul_f32_e32 v2, v2, v6
	v_lshlrev_b32_e32 v6, 16, v3
	v_lshlrev_b32_e32 v7, 16, v101
	v_mul_f32_e32 v9, v6, v7
	v_and_b32_e32 v6, 0xffff0000, v101
	v_and_b32_e32 v3, 0xffff0000, v3
	v_mul_f32_e32 v3, v3, v6
	v_lshlrev_b32_e32 v6, 16, v4
	v_lshlrev_b32_e32 v7, 16, v102
	v_mul_f32_e32 v10, v6, v7
	v_and_b32_e32 v6, 0xffff0000, v102
	v_and_b32_e32 v4, 0xffff0000, v4
	v_mul_f32_e32 v4, v4, v6
	v_lshlrev_b32_e32 v6, 16, v5
	v_lshlrev_b32_e32 v7, 16, v103
	v_mul_f32_e32 v11, v6, v7
	v_and_b32_e32 v6, 0xffff0000, v103
	v_and_b32_e32 v5, 0xffff0000, v5
	v_mul_f32_e32 v5, v5, v6
	v_lshl_add_u64 v[6:7], s[40:41], 0, v[218:219]
	v_lshlrev_b64 v[6:7], 13, v[6:7]
	v_lshl_add_u64 v[0:1], v[0:1], 0, v[6:7]
	v_cvt_pk_bf16_f32 v2, v8, v2
	v_cvt_pk_bf16_f32 v3, v9, v3
	v_cvt_pk_bf16_f32 v4, v10, v4
	v_cvt_pk_bf16_f32 v5, v11, v5
	global_store_dwordx4 v[0:1], v[2:5], off
	s_branch .LBB0_1199
.Lp5_lastwait:
	s_waitcnt vmcnt(0)
	s_branch .LBB0_1263
